# latent attention: both K/Q fragment read pairs of each S tile issued together (spare quads), fewer exposed lgkmcnt(0) stalls
# speedup vs baseline: 1.0055x; 1.0033x over previous
.LBB0_892:
	v_lshl_or_b32 v172, s12, 14, v159
	v_add_u32_e32 v2, v172, v158
	v_add_u32_e32 v246, v172, v160
	ds_read_b128 v[2:5], v2 offset:4096
	ds_read_b128 v[144:147], v157 offset:49152
	ds_read_b128 v[246:249], v246 offset:4096
	ds_read_b128 v[10:13], v157 offset:57344
	s_waitcnt lgkmcnt(2)
	s_nop 0
	v_mfma_f32_32x32x16_f16 v[128:143], v[2:5], v[144:147], v[194:209]
	s_waitcnt lgkmcnt(0)
	v_mfma_f32_32x32x16_f16 v[128:143], v[246:249], v[10:13], v[128:143]
	v_max_f32_e32 v2, v81, v81
	v_max_f32_e32 v3, v80, v80
	v_max_f32_e32 v2, v3, v2
	v_max3_f32 v2, v2, v82, v83
	v_max3_f32 v2, v2, v84, v85
	v_max3_f32 v2, v2, v86, v87
	v_max3_f32 v2, v2, v88, v89
	v_max3_f32 v2, v2, v90, v91
	v_max3_f32 v2, v2, v92, v93
	v_max3_f32 v2, v2, v94, v95
	v_cmp_lt_f32_e32 vcc, s61, v2
	s_cbranch_vccz .LBB0_894
	ds_bpermute_b32 v3, v153, v2
	s_waitcnt lgkmcnt(0)
	v_max_f32_e32 v3, v3, v3
	v_max_f32_e32 v2, v2, v3
	v_max_f32_e32 v2, v2, v2
	v_max_f32_e32 v2, 0, v2
	v_exp_f32_e64 v4, -v2
	v_add_f32_e32 v169, v169, v2
	v_pk_add_f32 v[80:81], v[80:81], v[2:3] op_sel_hi:[1,0] neg_lo:[0,1] neg_hi:[0,1]
	v_pk_add_f32 v[82:83], v[82:83], v[2:3] op_sel_hi:[1,0] neg_lo:[0,1] neg_hi:[0,1]
	v_mul_f32_e32 v171, v171, v4
	v_pk_add_f32 v[84:85], v[84:85], v[2:3] op_sel_hi:[1,0] neg_lo:[0,1] neg_hi:[0,1]
	v_pk_add_f32 v[86:87], v[86:87], v[2:3] op_sel_hi:[1,0] neg_lo:[0,1] neg_hi:[0,1]
	v_pk_add_f32 v[88:89], v[88:89], v[2:3] op_sel_hi:[1,0] neg_lo:[0,1] neg_hi:[0,1]
	v_pk_add_f32 v[90:91], v[90:91], v[2:3] op_sel_hi:[1,0] neg_lo:[0,1] neg_hi:[0,1]
	v_pk_add_f32 v[92:93], v[92:93], v[2:3] op_sel_hi:[1,0] neg_lo:[0,1] neg_hi:[0,1]
	v_pk_add_f32 v[94:95], v[94:95], v[2:3] op_sel_hi:[1,0] neg_lo:[0,1] neg_hi:[0,1]
	v_sub_f32_e32 v143, v143, v2
	v_sub_f32_e32 v142, v142, v2
	v_sub_f32_e32 v141, v141, v2
	v_sub_f32_e32 v140, v140, v2
	v_sub_f32_e32 v139, v139, v2
	v_sub_f32_e32 v138, v138, v2
	v_sub_f32_e32 v137, v137, v2
	v_sub_f32_e32 v136, v136, v2
	v_sub_f32_e32 v135, v135, v2
	v_sub_f32_e32 v134, v134, v2
	v_sub_f32_e32 v133, v133, v2
	v_sub_f32_e32 v132, v132, v2
	v_sub_f32_e32 v131, v131, v2
	v_sub_f32_e32 v130, v130, v2
	v_sub_f32_e32 v129, v129, v2
	v_sub_f32_e32 v128, v128, v2
	v_pk_mul_f32 v[30:31], v[30:31], v[4:5] op_sel_hi:[1,0]
	v_pk_mul_f32 v[28:29], v[28:29], v[4:5] op_sel_hi:[1,0]
	v_pk_mul_f32 v[26:27], v[26:27], v[4:5] op_sel_hi:[1,0]
	v_pk_mul_f32 v[24:25], v[24:25], v[4:5] op_sel_hi:[1,0]
	v_pk_mul_f32 v[22:23], v[22:23], v[4:5] op_sel_hi:[1,0]
	v_pk_mul_f32 v[20:21], v[20:21], v[4:5] op_sel_hi:[1,0]
	v_pk_mul_f32 v[18:19], v[18:19], v[4:5] op_sel_hi:[1,0]
	v_pk_mul_f32 v[16:17], v[16:17], v[4:5] op_sel_hi:[1,0]
	v_pk_mul_f32 v[46:47], v[46:47], v[4:5] op_sel_hi:[1,0]
	v_pk_mul_f32 v[44:45], v[44:45], v[4:5] op_sel_hi:[1,0]
	v_pk_mul_f32 v[42:43], v[42:43], v[4:5] op_sel_hi:[1,0]
	v_pk_mul_f32 v[40:41], v[40:41], v[4:5] op_sel_hi:[1,0]
	v_pk_mul_f32 v[38:39], v[38:39], v[4:5] op_sel_hi:[1,0]
	v_pk_mul_f32 v[36:37], v[36:37], v[4:5] op_sel_hi:[1,0]
	v_pk_mul_f32 v[34:35], v[34:35], v[4:5] op_sel_hi:[1,0]
	v_pk_mul_f32 v[32:33], v[32:33], v[4:5] op_sel_hi:[1,0]
	v_sub_f32_e32 v194, v194, v2
	v_sub_f32_e32 v195, v195, v2
	v_sub_f32_e32 v196, v196, v2
	v_sub_f32_e32 v197, v197, v2
	v_sub_f32_e32 v198, v198, v2
	v_sub_f32_e32 v199, v199, v2
	v_sub_f32_e32 v200, v200, v2
	v_sub_f32_e32 v201, v201, v2
	v_sub_f32_e32 v202, v202, v2
	v_sub_f32_e32 v203, v203, v2
	v_sub_f32_e32 v204, v204, v2
	v_sub_f32_e32 v205, v205, v2
	v_sub_f32_e32 v206, v206, v2
	v_sub_f32_e32 v207, v207, v2
	v_sub_f32_e32 v208, v208, v2
	v_sub_f32_e32 v209, v209, v2
	s_nop 1
.LBB0_894:
	v_exp_f32_e32 v173, v80
	v_add_u32_e32 v80, v172, v161
	ds_read2st64_b64 v[112:115], v80 offset0:16 offset1:24
	v_add_u32_e32 v80, v172, v162
	v_exp_f32_e32 v177, v84
	v_exp_f32_e32 v178, v85
	v_exp_f32_e32 v179, v86
	v_exp_f32_e32 v180, v87
	ds_read2st64_b64 v[84:87], v80 offset0:16 offset1:24
	v_exp_f32_e32 v174, v81
	v_exp_f32_e32 v175, v82
	v_exp_f32_e32 v176, v83
	v_exp_f32_e32 v185, v92
	v_exp_f32_e32 v186, v93
	v_exp_f32_e32 v187, v94
	v_exp_f32_e32 v188, v95
	s_waitcnt lgkmcnt(0)
	v_mov_b32_e32 v92, v112
	v_mov_b32_e32 v93, v113
	v_mov_b32_e32 v94, v84
	v_mov_b32_e32 v95, v85
	v_mov_b32_e32 v84, v114
	v_mov_b32_e32 v85, v115
	v_add_u32_e32 v80, v172, v163
	ds_read2st64_b64 v[116:119], v80 offset0:16 offset1:24
	v_add_u32_e32 v80, v172, v164
	ds_read2st64_b64 v[80:83], v80 offset0:16 offset1:24
	v_cvt_pkrtz_f16_f32 v2, v173, v174
	v_cvt_pkrtz_f16_f32 v3, v175, v176
	v_cvt_pkrtz_f16_f32 v4, v177, v178
	v_cvt_pkrtz_f16_f32 v5, v179, v180
	v_exp_f32_e32 v181, v88
	v_exp_f32_e32 v182, v89
	v_mfma_f32_32x32x16_f16 v[16:31], v[92:95], v[2:5], v[16:31]
	v_exp_f32_e32 v183, v90
	v_exp_f32_e32 v184, v91
	s_waitcnt lgkmcnt(0)
	v_mov_b32_e32 v88, v116
	v_mov_b32_e32 v89, v117
	v_mov_b32_e32 v90, v80
	v_mov_b32_e32 v91, v81
	v_mov_b32_e32 v80, v118
	v_mfma_f32_32x32x16_f16 v[32:47], v[84:87], v[2:5], v[32:47]
	v_mov_b32_e32 v81, v119
	v_cvt_pkrtz_f16_f32 v6, v181, v182
	v_cvt_pkrtz_f16_f32 v7, v183, v184
	v_cvt_pkrtz_f16_f32 v8, v185, v186
	v_cvt_pkrtz_f16_f32 v9, v187, v188
	v_add_u32_e32 v2, v172, v156
	v_add_u32_e32 v246, v172, v155
	v_mfma_f32_32x32x16_f16 v[16:31], v[88:91], v[6:9], v[16:31]
	v_mfma_f32_32x32x16_f16 v[32:47], v[80:83], v[6:9], v[32:47]
	ds_read_b128 v[2:5], v2 offset:4096
	ds_read_b128 v[6:9], v154 offset:16384
	ds_read_b128 v[190:193], v246 offset:4096
	ds_read_b128 v[250:253], v154 offset:24576
	v_max_f32_e32 v189, v97, v97
	s_waitcnt lgkmcnt(2)
	v_mfma_f32_32x32x16_f16 v[112:127], v[2:5], v[6:9], v[230:245]
	s_waitcnt lgkmcnt(0)
	v_mfma_f32_32x32x16_f16 v[112:127], v[190:193], v[250:253], v[112:127]
	v_max_f32_e32 v190, v96, v96
	v_max_f32_e32 v189, v190, v189
	v_max3_f32 v189, v189, v98, v99
	v_max3_f32 v189, v189, v100, v101
	v_max3_f32 v189, v189, v102, v103
	v_max3_f32 v189, v189, v104, v105
	v_max3_f32 v189, v189, v106, v107
	v_max3_f32 v189, v189, v108, v109
	v_max3_f32 v189, v189, v110, v111
	v_cmp_lt_f32_e32 vcc, s61, v189
	s_cbranch_vccz .LBB0_896
	ds_bpermute_b32 v190, v153, v189
	s_waitcnt lgkmcnt(0)
	v_max_f32_e32 v190, v190, v190
	v_max_f32_e32 v189, v189, v190
	v_max_f32_e32 v189, v189, v189
	v_max_f32_e32 v190, 0, v189
	v_exp_f32_e64 v192, -v190
	v_add_f32_e32 v168, v168, v190
	v_pk_add_f32 v[96:97], v[96:97], v[190:191] op_sel_hi:[1,0] neg_lo:[0,1] neg_hi:[0,1]
	v_pk_add_f32 v[98:99], v[98:99], v[190:191] op_sel_hi:[1,0] neg_lo:[0,1] neg_hi:[0,1]
	v_mul_f32_e32 v170, v170, v192
	v_pk_add_f32 v[100:101], v[100:101], v[190:191] op_sel_hi:[1,0] neg_lo:[0,1] neg_hi:[0,1]
	v_pk_add_f32 v[102:103], v[102:103], v[190:191] op_sel_hi:[1,0] neg_lo:[0,1] neg_hi:[0,1]
	v_pk_add_f32 v[104:105], v[104:105], v[190:191] op_sel_hi:[1,0] neg_lo:[0,1] neg_hi:[0,1]
	v_pk_add_f32 v[106:107], v[106:107], v[190:191] op_sel_hi:[1,0] neg_lo:[0,1] neg_hi:[0,1]
	v_pk_add_f32 v[108:109], v[108:109], v[190:191] op_sel_hi:[1,0] neg_lo:[0,1] neg_hi:[0,1]
	v_pk_add_f32 v[110:111], v[110:111], v[190:191] op_sel_hi:[1,0] neg_lo:[0,1] neg_hi:[0,1]
	v_sub_f32_e32 v127, v127, v190
	v_sub_f32_e32 v126, v126, v190
	v_sub_f32_e32 v125, v125, v190
	v_sub_f32_e32 v124, v124, v190
	v_sub_f32_e32 v123, v123, v190
	v_sub_f32_e32 v122, v122, v190
	v_sub_f32_e32 v121, v121, v190
	v_sub_f32_e32 v120, v120, v190
	v_sub_f32_e32 v119, v119, v190
	v_sub_f32_e32 v118, v118, v190
	v_sub_f32_e32 v117, v117, v190
	v_sub_f32_e32 v116, v116, v190
	v_sub_f32_e32 v115, v115, v190
	v_sub_f32_e32 v114, v114, v190
	v_sub_f32_e32 v113, v113, v190
	v_sub_f32_e32 v112, v112, v190
	v_pk_mul_f32 v[62:63], v[62:63], v[192:193] op_sel_hi:[1,0]
	v_pk_mul_f32 v[60:61], v[60:61], v[192:193] op_sel_hi:[1,0]
	v_pk_mul_f32 v[58:59], v[58:59], v[192:193] op_sel_hi:[1,0]
	v_pk_mul_f32 v[56:57], v[56:57], v[192:193] op_sel_hi:[1,0]
	v_pk_mul_f32 v[54:55], v[54:55], v[192:193] op_sel_hi:[1,0]
	v_pk_mul_f32 v[52:53], v[52:53], v[192:193] op_sel_hi:[1,0]
	v_pk_mul_f32 v[50:51], v[50:51], v[192:193] op_sel_hi:[1,0]
	v_pk_mul_f32 v[48:49], v[48:49], v[192:193] op_sel_hi:[1,0]
	v_pk_mul_f32 v[78:79], v[78:79], v[192:193] op_sel_hi:[1,0]
	v_pk_mul_f32 v[76:77], v[76:77], v[192:193] op_sel_hi:[1,0]
	v_pk_mul_f32 v[74:75], v[74:75], v[192:193] op_sel_hi:[1,0]
	v_pk_mul_f32 v[72:73], v[72:73], v[192:193] op_sel_hi:[1,0]
	v_pk_mul_f32 v[70:71], v[70:71], v[192:193] op_sel_hi:[1,0]
	v_pk_mul_f32 v[68:69], v[68:69], v[192:193] op_sel_hi:[1,0]
	v_pk_mul_f32 v[66:67], v[66:67], v[192:193] op_sel_hi:[1,0]
	v_pk_mul_f32 v[64:65], v[64:65], v[192:193] op_sel_hi:[1,0]
	v_sub_f32_e32 v230, v230, v190
	v_sub_f32_e32 v231, v231, v190
	v_sub_f32_e32 v232, v232, v190
	v_sub_f32_e32 v233, v233, v190
	v_sub_f32_e32 v234, v234, v190
	v_sub_f32_e32 v235, v235, v190
	v_sub_f32_e32 v236, v236, v190
	v_sub_f32_e32 v237, v237, v190
	v_sub_f32_e32 v238, v238, v190
	v_sub_f32_e32 v239, v239, v190
	v_sub_f32_e32 v240, v240, v190
	v_sub_f32_e32 v241, v241, v190
	v_sub_f32_e32 v242, v242, v190
	v_sub_f32_e32 v243, v243, v190
	v_sub_f32_e32 v244, v244, v190
	v_sub_f32_e32 v245, v245, v190
	s_nop 1
.LBB0_896:
	v_add_f32_e32 v173, 0, v173
	v_add_f32_e32 v173, v174, v173
	v_add_f32_e32 v173, v175, v173
	v_add_f32_e32 v173, v176, v173
	v_add_f32_e32 v173, v177, v173
	v_add_f32_e32 v173, v178, v173
	v_add_f32_e32 v173, v179, v173
	v_add_f32_e32 v173, v180, v173
	v_add_f32_e32 v173, v181, v173
	v_add_f32_e32 v173, v182, v173
	v_add_f32_e32 v173, v183, v173
	v_add_f32_e32 v173, v184, v173
	v_add_f32_e32 v173, v185, v173
	v_exp_f32_e32 v96, v96
	v_exp_f32_e32 v97, v97
	v_exp_f32_e32 v98, v98
	v_exp_f32_e32 v99, v99
	v_exp_f32_e32 v100, v100
	v_exp_f32_e32 v101, v101
	v_exp_f32_e32 v102, v102
	v_exp_f32_e32 v103, v103
	v_add_f32_e32 v173, v186, v173
	v_add_f32_e32 v173, v187, v173
	v_add_f32_e32 v173, v188, v173
	v_add_f32_e32 v171, v171, v173
	v_add_u32_e32 v173, s11, v159
	v_cvt_pkrtz_f16_f32 v174, v96, v97
	v_cvt_pkrtz_f16_f32 v175, v98, v99
	v_cvt_pkrtz_f16_f32 v176, v100, v101
	v_cvt_pkrtz_f16_f32 v177, v102, v103
	v_exp_f32_e32 v104, v104
	v_exp_f32_e32 v105, v105
	v_mfma_f32_32x32x16_f16 v[48:63], v[92:95], v[174:177], v[48:63]
	v_exp_f32_e32 v106, v106
	v_exp_f32_e32 v107, v107
	v_exp_f32_e32 v108, v108
	v_exp_f32_e32 v109, v109
	v_exp_f32_e32 v110, v110
	v_exp_f32_e32 v111, v111
	v_cvt_pkrtz_f16_f32 v178, v104, v105
	v_mfma_f32_32x32x16_f16 v[64:79], v[84:87], v[174:177], v[64:79]
	v_add_u32_e32 v174, v173, v158
	ds_read_b128 v[174:177], v174
	v_add_u32_e32 v246, v173, v160
	ds_read_b128 v[246:249], v246
	v_cvt_pkrtz_f16_f32 v179, v106, v107
	v_cvt_pkrtz_f16_f32 v180, v108, v109
	v_cvt_pkrtz_f16_f32 v181, v110, v111
	s_nop 1
	v_mfma_f32_32x32x16_f16 v[64:79], v[80:83], v[178:181], v[64:79]
	v_mfma_f32_32x32x16_f16 v[48:63], v[88:91], v[178:181], v[48:63]
	s_waitcnt lgkmcnt(0)
	s_nop 0
	v_mfma_f32_32x32x16_f16 v[80:95], v[174:177], v[144:147], v[194:209]
	v_mfma_f32_32x32x16_f16 v[80:95], v[246:249], v[10:13], v[80:95]
	v_max_f32_e32 v10, v129, v129
	v_max_f32_e32 v11, v128, v128
	v_max_f32_e32 v10, v11, v10
	v_max3_f32 v10, v10, v130, v131
	v_max3_f32 v10, v10, v132, v133
	v_max3_f32 v10, v10, v134, v135
	v_max3_f32 v10, v10, v136, v137
	v_max3_f32 v10, v10, v138, v139
	v_max3_f32 v10, v10, v140, v141
	v_max3_f32 v10, v10, v142, v143
	v_cmp_lt_f32_e32 vcc, s61, v10
	s_cbranch_vccz .LBB0_898
	ds_bpermute_b32 v11, v153, v10
	s_waitcnt lgkmcnt(0)
	v_max_f32_e32 v11, v11, v11
	v_max_f32_e32 v10, v10, v11
	v_max_f32_e32 v10, v10, v10
	v_max_f32_e32 v10, 0, v10
	v_exp_f32_e64 v12, -v10
	v_add_f32_e32 v169, v169, v10
	v_pk_add_f32 v[128:129], v[128:129], v[10:11] op_sel_hi:[1,0] neg_lo:[0,1] neg_hi:[0,1]
	v_pk_add_f32 v[130:131], v[130:131], v[10:11] op_sel_hi:[1,0] neg_lo:[0,1] neg_hi:[0,1]
	v_mul_f32_e32 v171, v171, v12
	v_pk_add_f32 v[132:133], v[132:133], v[10:11] op_sel_hi:[1,0] neg_lo:[0,1] neg_hi:[0,1]
	v_pk_add_f32 v[134:135], v[134:135], v[10:11] op_sel_hi:[1,0] neg_lo:[0,1] neg_hi:[0,1]
	v_pk_add_f32 v[136:137], v[136:137], v[10:11] op_sel_hi:[1,0] neg_lo:[0,1] neg_hi:[0,1]
	v_pk_add_f32 v[138:139], v[138:139], v[10:11] op_sel_hi:[1,0] neg_lo:[0,1] neg_hi:[0,1]
	v_pk_add_f32 v[140:141], v[140:141], v[10:11] op_sel_hi:[1,0] neg_lo:[0,1] neg_hi:[0,1]
	v_pk_add_f32 v[142:143], v[142:143], v[10:11] op_sel_hi:[1,0] neg_lo:[0,1] neg_hi:[0,1]
	v_sub_f32_e32 v95, v95, v10
	v_sub_f32_e32 v94, v94, v10
	v_sub_f32_e32 v93, v93, v10
	v_sub_f32_e32 v92, v92, v10
	v_sub_f32_e32 v91, v91, v10
	v_sub_f32_e32 v90, v90, v10
	v_sub_f32_e32 v89, v89, v10
	v_sub_f32_e32 v88, v88, v10
	v_sub_f32_e32 v87, v87, v10
	v_sub_f32_e32 v86, v86, v10
	v_sub_f32_e32 v85, v85, v10
	v_sub_f32_e32 v84, v84, v10
	v_sub_f32_e32 v83, v83, v10
	v_sub_f32_e32 v82, v82, v10
	v_sub_f32_e32 v81, v81, v10
	v_sub_f32_e32 v80, v80, v10
	v_pk_mul_f32 v[30:31], v[30:31], v[12:13] op_sel_hi:[1,0]
	v_pk_mul_f32 v[28:29], v[28:29], v[12:13] op_sel_hi:[1,0]
	v_pk_mul_f32 v[26:27], v[26:27], v[12:13] op_sel_hi:[1,0]
	v_pk_mul_f32 v[24:25], v[24:25], v[12:13] op_sel_hi:[1,0]
	v_pk_mul_f32 v[22:23], v[22:23], v[12:13] op_sel_hi:[1,0]
	v_pk_mul_f32 v[20:21], v[20:21], v[12:13] op_sel_hi:[1,0]
	v_pk_mul_f32 v[18:19], v[18:19], v[12:13] op_sel_hi:[1,0]
	v_pk_mul_f32 v[16:17], v[16:17], v[12:13] op_sel_hi:[1,0]
	v_pk_mul_f32 v[46:47], v[46:47], v[12:13] op_sel_hi:[1,0]
	v_pk_mul_f32 v[44:45], v[44:45], v[12:13] op_sel_hi:[1,0]
	v_pk_mul_f32 v[42:43], v[42:43], v[12:13] op_sel_hi:[1,0]
	v_pk_mul_f32 v[40:41], v[40:41], v[12:13] op_sel_hi:[1,0]
	v_pk_mul_f32 v[38:39], v[38:39], v[12:13] op_sel_hi:[1,0]
	v_pk_mul_f32 v[36:37], v[36:37], v[12:13] op_sel_hi:[1,0]
	v_pk_mul_f32 v[34:35], v[34:35], v[12:13] op_sel_hi:[1,0]
	v_pk_mul_f32 v[32:33], v[32:33], v[12:13] op_sel_hi:[1,0]
	v_sub_f32_e32 v194, v194, v10
	v_sub_f32_e32 v195, v195, v10
	v_sub_f32_e32 v196, v196, v10
	v_sub_f32_e32 v197, v197, v10
	v_sub_f32_e32 v198, v198, v10
	v_sub_f32_e32 v199, v199, v10
	v_sub_f32_e32 v200, v200, v10
	v_sub_f32_e32 v201, v201, v10
	v_sub_f32_e32 v202, v202, v10
	v_sub_f32_e32 v203, v203, v10
	v_sub_f32_e32 v204, v204, v10
	v_sub_f32_e32 v205, v205, v10
	v_sub_f32_e32 v206, v206, v10
	v_sub_f32_e32 v207, v207, v10
	v_sub_f32_e32 v208, v208, v10
	v_sub_f32_e32 v209, v209, v10
	s_nop 1
.LBB0_898:
	v_add_f32_e32 v10, 0, v96
	v_add_f32_e32 v10, v97, v10
	v_add_f32_e32 v10, v98, v10
	v_add_f32_e32 v10, v99, v10
	v_add_f32_e32 v10, v100, v10
	v_add_f32_e32 v10, v101, v10
	v_add_f32_e32 v10, v102, v10
	v_add_f32_e32 v10, v103, v10
	v_add_f32_e32 v10, v104, v10
	v_add_f32_e32 v10, v105, v10
	v_add_f32_e32 v10, v106, v10
	v_add_f32_e32 v10, v107, v10
	v_add_f32_e32 v10, v108, v10
	v_add_f32_e32 v10, v109, v10
	v_add_f32_e32 v10, v110, v10
	v_add_f32_e32 v10, v111, v10
	v_add_f32_e32 v144, v170, v10
	v_add_u32_e32 v10, v172, v166
	ds_read2st64_b64 v[104:107], v10 offset0:16 offset1:24
	v_add_u32_e32 v10, v172, v167
	v_exp_f32_e32 v145, v128
	v_exp_f32_e32 v146, v129
	v_exp_f32_e32 v147, v130
	v_exp_f32_e32 v170, v131
	ds_read2st64_b64 v[128:131], v10 offset0:16 offset1:24
	v_exp_f32_e32 v174, v132
	v_exp_f32_e32 v175, v133
	v_exp_f32_e32 v176, v134
	v_exp_f32_e32 v177, v135
	v_exp_f32_e32 v178, v136
	v_exp_f32_e32 v179, v137
	v_exp_f32_e32 v180, v138
	v_exp_f32_e32 v181, v139
	s_waitcnt lgkmcnt(0)
	v_mov_b32_e32 v136, v104
	v_mov_b32_e32 v137, v105
	v_mov_b32_e32 v138, v128
	v_mov_b32_e32 v139, v129
	v_mov_b32_e32 v128, v106
	v_mov_b32_e32 v129, v107
	v_add_u32_e32 v10, v172, v1
	ds_read2st64_b64 v[108:111], v10 offset0:16 offset1:24
	v_add_u32_e32 v10, v172, v165
	ds_read2st64_b64 v[10:13], v10 offset0:16 offset1:24
	v_cvt_pkrtz_f16_f32 v96, v145, v146
	v_cvt_pkrtz_f16_f32 v97, v147, v170
	v_cvt_pkrtz_f16_f32 v98, v174, v175
	v_cvt_pkrtz_f16_f32 v99, v176, v177
	v_add_u32_e32 v172, v173, v155
	v_add_u32_e32 v173, v173, v156
	v_mfma_f32_32x32x16_f16 v[16:31], v[136:139], v[96:99], v[16:31]
	ds_read_b128 v[182:185], v173
	ds_read_b128 v[246:249], v172
	v_exp_f32_e32 v140, v140
	v_exp_f32_e32 v141, v141
	v_exp_f32_e32 v142, v142
	v_exp_f32_e32 v143, v143
	s_waitcnt lgkmcnt(0)
	v_mov_b32_e32 v132, v108
	v_mov_b32_e32 v133, v109
	v_mfma_f32_32x32x16_f16 v[32:47], v[128:131], v[96:99], v[32:47]
	v_mov_b32_e32 v134, v10
	v_mov_b32_e32 v135, v11
	v_mov_b32_e32 v10, v110
	v_mov_b32_e32 v11, v111
	v_cvt_pkrtz_f16_f32 v100, v178, v179
	v_cvt_pkrtz_f16_f32 v101, v180, v181
	v_cvt_pkrtz_f16_f32 v102, v140, v141
	v_cvt_pkrtz_f16_f32 v103, v142, v143
	s_nop 1
	v_mfma_f32_32x32x16_f16 v[16:31], v[132:135], v[100:103], v[16:31]
	s_nop 0
	v_mfma_f32_32x32x16_f16 v[32:47], v[10:13], v[100:103], v[32:47]
	s_nop 1
	v_mfma_f32_32x32x16_f16 v[96:111], v[182:185], v[6:9], v[230:245]
	v_mfma_f32_32x32x16_f16 v[96:111], v[246:249], v[250:253], v[96:111]
	v_max_f32_e32 v2, v113, v113
	v_max_f32_e32 v3, v112, v112
	v_max_f32_e32 v2, v3, v2
	v_max3_f32 v2, v2, v114, v115
	v_max3_f32 v2, v2, v116, v117
	v_max3_f32 v2, v2, v118, v119
	v_max3_f32 v2, v2, v120, v121
	v_max3_f32 v2, v2, v122, v123
	v_max3_f32 v2, v2, v124, v125
	v_max3_f32 v2, v2, v126, v127
	v_cmp_lt_f32_e32 vcc, s61, v2
	s_cbranch_vccz .LBB0_900
	ds_bpermute_b32 v3, v153, v2
	s_waitcnt lgkmcnt(0)
	v_max_f32_e32 v3, v3, v3
	v_max_f32_e32 v2, v2, v3
	v_max_f32_e32 v2, v2, v2
	v_max_f32_e32 v2, 0, v2
	v_exp_f32_e64 v4, -v2
	v_add_f32_e32 v168, v168, v2
	v_pk_add_f32 v[112:113], v[112:113], v[2:3] op_sel_hi:[1,0] neg_lo:[0,1] neg_hi:[0,1]
	v_pk_add_f32 v[114:115], v[114:115], v[2:3] op_sel_hi:[1,0] neg_lo:[0,1] neg_hi:[0,1]
	v_mul_f32_e32 v144, v144, v4
	v_pk_add_f32 v[116:117], v[116:117], v[2:3] op_sel_hi:[1,0] neg_lo:[0,1] neg_hi:[0,1]
	v_pk_add_f32 v[118:119], v[118:119], v[2:3] op_sel_hi:[1,0] neg_lo:[0,1] neg_hi:[0,1]
	v_pk_add_f32 v[120:121], v[120:121], v[2:3] op_sel_hi:[1,0] neg_lo:[0,1] neg_hi:[0,1]
	v_pk_add_f32 v[122:123], v[122:123], v[2:3] op_sel_hi:[1,0] neg_lo:[0,1] neg_hi:[0,1]
	v_pk_add_f32 v[124:125], v[124:125], v[2:3] op_sel_hi:[1,0] neg_lo:[0,1] neg_hi:[0,1]
	v_pk_add_f32 v[126:127], v[126:127], v[2:3] op_sel_hi:[1,0] neg_lo:[0,1] neg_hi:[0,1]
	v_sub_f32_e32 v111, v111, v2
	v_sub_f32_e32 v110, v110, v2
	v_sub_f32_e32 v109, v109, v2
	v_sub_f32_e32 v108, v108, v2
	v_sub_f32_e32 v107, v107, v2
	v_sub_f32_e32 v106, v106, v2
	v_sub_f32_e32 v105, v105, v2
	v_sub_f32_e32 v104, v104, v2
	v_sub_f32_e32 v103, v103, v2
	v_sub_f32_e32 v102, v102, v2
	v_sub_f32_e32 v101, v101, v2
	v_sub_f32_e32 v100, v100, v2
	v_sub_f32_e32 v99, v99, v2
	v_sub_f32_e32 v98, v98, v2
	v_sub_f32_e32 v97, v97, v2
	v_sub_f32_e32 v96, v96, v2
	v_pk_mul_f32 v[62:63], v[62:63], v[4:5] op_sel_hi:[1,0]
	v_pk_mul_f32 v[60:61], v[60:61], v[4:5] op_sel_hi:[1,0]
	v_pk_mul_f32 v[58:59], v[58:59], v[4:5] op_sel_hi:[1,0]
	v_pk_mul_f32 v[56:57], v[56:57], v[4:5] op_sel_hi:[1,0]
	v_pk_mul_f32 v[54:55], v[54:55], v[4:5] op_sel_hi:[1,0]
	v_pk_mul_f32 v[52:53], v[52:53], v[4:5] op_sel_hi:[1,0]
	v_pk_mul_f32 v[50:51], v[50:51], v[4:5] op_sel_hi:[1,0]
	v_pk_mul_f32 v[48:49], v[48:49], v[4:5] op_sel_hi:[1,0]
	v_pk_mul_f32 v[78:79], v[78:79], v[4:5] op_sel_hi:[1,0]
	v_pk_mul_f32 v[76:77], v[76:77], v[4:5] op_sel_hi:[1,0]
	v_pk_mul_f32 v[74:75], v[74:75], v[4:5] op_sel_hi:[1,0]
	v_pk_mul_f32 v[72:73], v[72:73], v[4:5] op_sel_hi:[1,0]
	v_pk_mul_f32 v[70:71], v[70:71], v[4:5] op_sel_hi:[1,0]
	v_pk_mul_f32 v[68:69], v[68:69], v[4:5] op_sel_hi:[1,0]
	v_pk_mul_f32 v[66:67], v[66:67], v[4:5] op_sel_hi:[1,0]
	v_pk_mul_f32 v[64:65], v[64:65], v[4:5] op_sel_hi:[1,0]
	v_sub_f32_e32 v230, v230, v2
	v_sub_f32_e32 v231, v231, v2
	v_sub_f32_e32 v232, v232, v2
	v_sub_f32_e32 v233, v233, v2
	v_sub_f32_e32 v234, v234, v2
	v_sub_f32_e32 v235, v235, v2
	v_sub_f32_e32 v236, v236, v2
	v_sub_f32_e32 v237, v237, v2
	v_sub_f32_e32 v238, v238, v2
	v_sub_f32_e32 v239, v239, v2
	v_sub_f32_e32 v240, v240, v2
	v_sub_f32_e32 v241, v241, v2
	v_sub_f32_e32 v242, v242, v2
	v_sub_f32_e32 v243, v243, v2
	v_sub_f32_e32 v244, v244, v2
	v_sub_f32_e32 v245, v245, v2
	s_nop 1
